# mLSTM pass2 chunk loop: single loop-top vmcnt wait split into per-consumer counted waits (Q at top, numerators before first use, o-gate before sigmoid section)
# baseline (speedup 1.0000x reference)
; #define LAS __attribute__((address_space(3)))
; __device__ __forceinline__ void mlstm_pass2(const bf16_t* PR, const bf16_t* QC, const float* gain, bf16_t* Y, LAS unsigned char* lds,
;                                             float* NB, const float* DEN, const float* BC, const float* FIMG, const float* DSEG, int st_first, int st_stride) {
;     ...
;         const size_t rs0 = (size_t)b * SEQL + 64 * (8 * seg);
;         const int frow = tid >> 4, fch = tid & 15;
;         const bf16_t* pQ = QC + (rs0 + frow) * 512 + hm * 128 + 8 * fch;
;         const int wq = (w < 4) ? w : 0;
;         const float* pN = num_ptr(NB, rs0 + r, hm) + 32 * wq + 4 * h;
;         const bf16_t* pO = PR + (rs0 + r) * PW + PC_OM + hm * 128 + 32 * wq + 4 * h;
;         const float* pB = BC + (rs0 + r) * 4 + hm; const float* pD = DEN + (rs0 + r) * 4 + hm;
;         f32x4 gv[4];
; #pragma unroll
;         for (int g4 = 0; g4 < 4; ++g4) gv[g4] = *(const f32x4*)(gain + hm * 128 + 32 * wq + 8 * g4 + 4 * h);
;         u32x4 fQ[2]; f32x4 nv[2][4]; u32x2 ov[2][4]; float bcv[2], dnv[2];
; #pragma unroll
;         for (int p2 = 0; p2 < 2; ++p2) fQ[p2] = *(const u32x4*)(pQ + (size_t)32 * p2 * 512);
; #pragma unroll
;         for (int tt = 0; tt < 2; ++tt) { bcv[tt] = pB[tt * 32 * 4]; dnv[tt] = pD[tt * 32 * 4];
; #pragma unroll
;             for (int g4 = 0; g4 < 4; ++g4) { nv[tt][g4] = *(const f32x4*)(pN + (size_t)tt * 32 * 512 + 8 * g4); ov[tt][g4] = *(const u32x2*)(pO + (size_t)tt * 32 * PW + 8 * g4); } }
;         for (int cc = 0; cc < 8; ++cc) {
;             const size_t r0 = rs0 + 64 * cc;
; #pragma unroll
;             for (int p2 = 0; p2 < 2; ++p2) *(LAS u32x4*)(lds + ML_QT + (frow + 32 * p2) * KROW + 16 * fch) = fQ[p2];
;             __syncthreads();
;             if (cc < 7) { pQ += 64 * 512;
; #pragma unroll
;                 for (int p2 = 0; p2 < 2; ++p2) fQ[p2] = *(const u32x4*)(pQ + (size_t)32 * p2 * 512); }
;             f32x16 res[2];
;             if (w < 5) {
; #pragma unroll
;                 for (int tt = 0; tt < 2; ++tt) {
;                     const LAS unsigned char* qb0 = lds + ML_QT + (32 * tt + r) * KROW + 8 * h;
;                     f32x16 acc;
; #pragma unroll
;                     for (int e = 0; e < 16; ++e) acc[e] = 0.f;
; #pragma unroll
;                     for (int i = 0; i < 4; ++i)
; #pragma unroll
.LBB0_570:
	s_cmp_lt_i32 s33, 4
	s_cselect_b32 s98, s33, 0
	s_lshl_b32 s99, s51, 5
	s_add_i32 s98, s98, s99
	s_lshl_b32 s98, s98, 13
	v_readlane_b32 s100, v235, 2
	v_readlane_b32 s101, v235, 3
	s_nop 0
	s_add_u32 s100, s100, 0x4000000
	s_addc_u32 s101, s101, 0
	s_add_u32 s100, s100, s98
	s_addc_u32 s101, s101, 0
	s_add_u32 s98, s100, 0x1000
	s_addc_u32 s99, s101, 0
	v_mbcnt_lo_u32_b32 v204, -1, 0
	v_mbcnt_hi_u32_b32 v204, -1, v204
	v_lshlrev_b32_e32 v204, 4, v204
	s_and_b32 s54, s8, 3
	s_ashr_i32 s8, s51, 4
	s_ashr_i32 s9, s8, 31
	s_lshl_b64 s[0:1], s[8:9], 11
	s_lshl_b32 s2, s26, 9
	s_or_b32 s2, s0, s2
	s_mov_b32 s3, s1
	v_lshl_add_u64 v[0:1], s[2:3], 0, v[110:111]
	v_mov_b32_e32 v3, s1
	v_or_b32_e32 v2, s2, v104
	v_lshlrev_b64 v[0:1], 10, v[0:1]
	v_lshlrev_b64 v[4:5], 11, v[2:3]
	v_mov_b64_e32 v[6:7], s[10:11]
	v_lshl_add_u64 v[0:1], s[12:13], 0, v[0:1]
	s_lshl_b32 s26, s54, 8
	v_lshl_add_u64 v[4:5], s[14:15], 0, v[4:5]
	s_lshl_b32 s40, s54, 9
	s_mov_b32 s41, s27
	v_mad_u64_u32 v[6:7], s[52:53], v2, s44, v[6:7]
	v_lshl_add_u64 v[0:1], v[0:1], 0, s[26:27]
	v_lshl_add_u64 v[4:5], v[4:5], 0, s[40:41]
	v_mad_i32_i24 v7, s1, v193, v7
	v_lshl_add_u64 v[10:11], v[114:115], 0, s[40:41]
	v_lshl_add_u64 v[4:5], s[28:29], 2, v[4:5]
	v_lshl_add_u64 v[6:7], v[6:7], 0, s[26:27]
	global_load_dwordx4 v[60:63], v[10:11], off
	global_load_dwordx4 v[56:59], v[10:11], off offset:32
	global_load_dwordx4 v[52:55], v[10:11], off offset:64
	global_load_dwordx4 v[48:51], v[10:11], off offset:96
	v_lshl_add_u64 v[0:1], v[0:1], 0, v[106:107]
	v_lshlrev_b32_e32 v10, 2, v112
	v_mov_b32_e32 v11, v107
	v_lshl_add_u64 v[6:7], s[28:29], 1, v[6:7]
	v_lshl_add_u64 v[4:5], v[4:5], 0, v[10:11]
	global_load_dwordx4 v[80:83], v[0:1], off
	v_add_co_u32_e32 v0, vcc, s45, v0
	v_lshlrev_b32_e32 v10, 1, v112
	s_nop 0
	v_addc_co_u32_e32 v1, vcc, 0, v1, vcc
	v_lshl_add_u64 v[6:7], v[6:7], 0, v[10:11]
	v_lshlrev_b64 v[2:3], 4, v[2:3]
	v_add_co_u32_e32 v12, vcc, s46, v6
	v_lshl_add_u64 v[8:9], s[16:17], 0, v[2:3]
	v_lshl_add_u64 v[2:3], s[18:19], 0, v[2:3]
	s_lshl_b32 s52, s54, 2
	s_mov_b32 s53, s27
	v_addc_co_u32_e32 v13, vcc, 0, v7, vcc
	v_lshl_add_u64 v[2:3], v[2:3], 0, s[52:53]
	v_lshl_add_u64 v[10:11], v[6:7], 0, s[30:31]
	v_lshl_add_u64 v[8:9], v[8:9], 0, s[52:53]
	global_load_dwordx2 v[186:187], v[12:13], off offset:2048
	global_load_dwordx4 v[100:103], v204, s[100:101]
	global_load_dwordx4 v[96:99], v204, s[100:101] offset:1024
	global_load_dwordx4 v[92:95], v204, s[100:101] offset:2048
	global_load_dwordx4 v[88:91], v204, s[100:101] offset:3072
	global_load_dword v198, v[8:9], off
	global_load_dwordx2 v[172:173], v[10:11], off offset:32
	global_load_dword v196, v[8:9], off offset:512
	global_load_dwordx2 v[170:171], v[10:11], off offset:48
	global_load_dwordx4 v[84:87], v[0:1], off
	global_load_dword v188, v[2:3], off
	global_load_dwordx2 v[174:175], v[10:11], off offset:16
	global_load_dword v197, v[2:3], off offset:512
	v_add_co_u32_e32 v0, vcc, s47, v4
	s_and_b32 s41, s50, 3
	s_nop 0
	v_addc_co_u32_e32 v1, vcc, 0, v5, vcc
	v_add_co_u32_e32 v2, vcc, s48, v6
	s_lshl_b32 s53, s41, 9
	s_nop 0
	v_addc_co_u32_e32 v3, vcc, 0, v7, vcc
	global_load_dwordx4 v[76:79], v204, s[98:99]
	global_load_dwordx4 v[72:75], v204, s[98:99] offset:1024
	global_load_dwordx4 v[68:71], v204, s[98:99] offset:2048
	global_load_dwordx4 v[64:67], v204, s[98:99] offset:3072
	global_load_dwordx2 v[168:169], v[2:3], off offset:2048
	global_load_dwordx2 v[166:167], v[2:3], off offset:2064
	global_load_dwordx2 v[164:165], v[2:3], off offset:2080
	global_load_dwordx2 v[162:163], v[2:3], off offset:2096
	s_lshl_b32 s54, s54, 7
	v_add_u32_e32 v160, s54, v119
	s_or_b32 s54, s0, s53
	s_mov_b32 s55, s1
	v_lshl_add_u64 v[0:1], s[54:55], 0, v[110:111]
	s_lshl_b32 s41, s41, 20
	v_lshlrev_b64 v[176:177], 10, v[0:1]
	s_lshl_b64 s[8:9], s[8:9], 22
	v_or_b32_e32 v0, v116, v176
	s_or_b32 s8, s8, s41
	v_ashrrev_i32_e32 v161, 31, v160
	v_or_b32_e32 v176, s26, v0
	v_mov_b32_e32 v0, s8
	v_mov_b32_e32 v1, s9
	v_lshl_add_u64 v[0:1], v[160:161], 1, v[0:1]
	v_lshl_add_u64 v[178:179], v[122:123], 0, v[0:1]
	v_or_b32_e32 v0, s0, v104
	v_mov_b32_e32 v1, s1
	v_or_b32_e32 v0, s53, v0
	v_lshlrev_b64 v[2:3], 11, v[0:1]
	v_lshlrev_b64 v[182:183], 4, v[0:1]
	v_mad_u64_u32 v[0:1], s[8:9], v0, s44, v[126:127]
	v_or_b32_e32 v2, s40, v2
	v_mad_i32_i24 v1, s1, v193, v1
	v_lshl_add_u64 v[180:181], v[124:125], 0, v[2:3]
	v_or_b32_e32 v182, s52, v182
	v_lshl_add_u64 v[184:185], v[0:1], 0, s[26:27]
	s_mov_b64 s[0:1], 0
	s_waitcnt vmcnt(0)
	s_branch .LBB0_572
.Lp2_nostore:
	s_nop 0
.LBB0_571:
	s_add_u32 s0, s0, 0x20000
	s_addc_u32 s1, s1, 0
	v_lshl_add_u64 v[176:177], v[176:177], 0, s[34:35]
	v_lshl_add_u64 v[182:183], v[182:183], 0, s[36:37]
	s_cmp_eq_u32 s0, 0xe0000
	v_lshl_add_u64 v[184:185], v[184:185], 0, s[38:39]
	s_cbranch_scc1 .LBB0_593
.LBB0_572:
	v_lshl_add_u64 v[0:1], s[10:11], 0, v[176:177]
	v_add_co_u32_e32 v2, vcc, 0x19310000, v0
	s_waitcnt vmcnt(20) lgkmcnt(0)
	ds_write_b128 v194, v[80:83]
	ds_write_b128 v194, v[84:87] offset:8704
	v_addc_co_u32_e32 v3, vcc, 0, v1, vcc
	v_add_co_u32_e32 v0, vcc, 0x19318000, v0
	s_waitcnt lgkmcnt(0)
	s_barrier
	v_addc_co_u32_e32 v1, vcc, 0, v1, vcc
	global_load_dwordx4 v[80:83], v[2:3], off
	global_load_dwordx4 v[84:87], v[0:1], off
	s_and_b64 vcc, exec, s[6:7]
	s_cbranch_vccnz .LBB0_585
	s_and_b64 vcc, exec, s[22:23]
	s_cbranch_vccnz .Lp2_nvw4
	s_waitcnt vmcnt(18)
	s_branch .Lp2_nvj
.Lp2_nvw4:
	s_waitcnt vmcnt(10)
.Lp2_nvj:
	v_add_u32_e32 v199, v113, v121
	ds_read2_b64 v[0:3], v199 offset1:2
	ds_read2_b64 v[200:203], v199 offset0:4 offset1:6
	v_mul_f32_e32 v188, 0x3fb8aa3b, v188
	v_exp_f32_e32 v188, v188
	s_mov_b64 s[8:9], -1
	s_waitcnt lgkmcnt(0)
	v_mfma_f32_32x32x16_bf16 v[0:15], v[16:19], v[0:3], 0
	s_and_b64 vcc, exec, s[22:23]
	v_mfma_f32_32x32x16_bf16 v[0:15], v[20:23], v[200:203], v[0:15]
	ds_read2_b64 v[200:203], v199 offset0:8 offset1:10
	s_waitcnt lgkmcnt(0)
	v_mfma_f32_32x32x16_bf16 v[0:15], v[24:27], v[200:203], v[0:15]
	ds_read2_b64 v[200:203], v199 offset0:12 offset1:14
	s_waitcnt lgkmcnt(0)
	v_mfma_f32_32x32x16_bf16 v[0:15], v[28:31], v[200:203], v[0:15]
	ds_read2_b64 v[200:203], v199 offset0:16 offset1:18
	s_waitcnt lgkmcnt(0)
	v_mfma_f32_32x32x16_bf16 v[0:15], v[32:35], v[200:203], v[0:15]
	ds_read2_b64 v[200:203], v199 offset0:20 offset1:22
	s_waitcnt lgkmcnt(0)
	v_mfma_f32_32x32x16_bf16 v[0:15], v[36:39], v[200:203], v[0:15]
	ds_read2_b64 v[200:203], v199 offset0:24 offset1:26
	s_waitcnt lgkmcnt(0)
	v_mfma_f32_32x32x16_bf16 v[0:15], v[40:43], v[200:203], v[0:15]
	ds_read2_b64 v[200:203], v199 offset0:28 offset1:30
	s_waitcnt lgkmcnt(0)
	v_mfma_f32_32x32x16_bf16 v[0:15], v[44:47], v[200:203], v[0:15]
	s_cbranch_vccz .LBB0_577
	s_and_saveexec_b64 s[8:9], s[4:5]
	s_nop 9
	v_fmac_f32_e32 v198, v188, v0
	ds_write_b32 v105, v198 offset:62720
	s_or_b64 exec, exec, s[8:9]
	s_mov_b64 s[8:9], 0

; __device__ __forceinline__ float sigmoid_f(float x) { return __builtin_amdgcn_rcpf(1.f + __builtin_amdgcn_exp2f(-x * LOG2E)); }
; __device__ __forceinline__ void mlstm_pass2(const bf16_t* PR, const bf16_t* QC, const float* gain, bf16_t* Y, LAS unsigned char* lds,
;                                             float* NB, const float* DEN, const float* BC, const float* FIMG, const float* DSEG, int st_first, int st_stride) {
;     ...
;             if (cc < 7) { pN += (size_t)64 * 512; pB += 64 * 4; pD += 64 * 4;
; #pragma unroll
;                 for (int tt = 0; tt < 2; ++tt) { bcv[tt] = pB[tt * 32 * 4]; dnv[tt] = pD[tt * 32 * 4];
; #pragma unroll
;                     for (int g4 = 0; g4 < 4; ++g4) nv[tt][g4] = *(const f32x4*)(pN + (size_t)tt * 32 * 512 + 8 * g4); } }
;             __syncthreads();
;             if (w < 4) {
; #pragma unroll
;                 for (int tt = 0; tt < 2; ++tt) {
;                     const float dd = 1.f / fmaxf(fabsf(den_t[32 * tt + r]), 1.f); float ss = 0.f;
; #pragma unroll
;                     for (int g4 = 0; g4 < 4; ++g4) { const u32x2 o2 = ov[tt][g4];
;                         const float og[4] = {__uint_as_float(o2.x << 16), __uint_as_float(o2.x & 0xffff0000u), __uint_as_float(o2.y << 16), __uint_as_float(o2.y & 0xffff0000u)};
; #pragma unroll
;                         for (int e = 0; e < 4; ++e) { const float v = res[tt][4 * g4 + e] * dd * sigmoid_f(og[e]); res[tt][4 * g4 + e] = v; ss += v * v; } }
;                     ss += __shfl_xor(ss, 32);
;                     if (h == 0) ssq_t[64 * w + 32 * tt + r] = ss;
;                 }
.LBB0_585:
	s_nop 8
	v_lshl_add_u64 v[2:3], s[10:11], 0, v[182:183]
	v_add_co_u32_e32 v4, vcc, 0x1d400000, v2
	v_lshl_add_u64 v[0:1], v[180:181], 0, s[0:1]
	s_nop 0
	v_addc_co_u32_e32 v5, vcc, 0, v3, vcc
	v_add_co_u32_e32 v2, vcc, 0x1d300000, v2
	s_nop 1
	v_addc_co_u32_e32 v3, vcc, 0, v3, vcc
	v_add_co_u32_e32 v6, vcc, 0x4020000, v0
	s_nop 1
	v_addc_co_u32_e32 v7, vcc, 0, v1, vcc
	s_lshr_b32 s98, s0, 2
	s_add_u32 s98, s98, 0x8000
	s_add_u32 s98, s100, s98
	s_addc_u32 s99, s101, 0
	global_load_dwordx4 v[100:103], v204, s[98:99]
	global_load_dwordx4 v[96:99], v204, s[98:99] offset:1024
	global_load_dwordx4 v[92:95], v204, s[98:99] offset:2048
	global_load_dwordx4 v[88:91], v204, s[98:99] offset:3072
	global_load_dword v188, v[4:5], off offset:1024
	global_load_dword v198, v[2:3], off offset:1024
	global_load_dword v196, v[2:3], off offset:1536
	global_load_dword v197, v[4:5], off offset:1536
	v_add_co_u32_e32 v0, vcc, 0x4030000, v0
	s_nop 1
	v_addc_co_u32_e32 v1, vcc, 0, v1, vcc
	s_add_u32 s98, s98, 0x1000
	s_addc_u32 s99, s99, 0
	global_load_dwordx4 v[76:79], v204, s[98:99]
	global_load_dwordx4 v[72:75], v204, s[98:99] offset:1024
	global_load_dwordx4 v[68:71], v204, s[98:99] offset:2048
	global_load_dwordx4 v[64:67], v204, s[98:99] offset:3072
	v_cndmask_b32_e64 v0, 0, 1, s[24:25]
	v_cmp_ne_u32_e64 s[8:9], 1, v0
	s_andn2_b64 vcc, exec, s[24:25]
	s_waitcnt lgkmcnt(0)
	s_barrier
	s_cbranch_vccnz .LBB0_591
	s_waitcnt vmcnt(22)
	ds_read_b32 v0, v105 offset:62720
	v_and_b32_e32 v2, 64, v195
	v_xor_b32_e32 v1, 32, v195
	v_add_u32_e32 v2, 64, v2
	v_cmp_lt_i32_e32 vcc, v1, v2
	s_waitcnt lgkmcnt(0)
	v_max_f32_e64 v0, |v0|, |v0|
	v_max_f32_e32 v3, 1.0, v0
	v_div_scale_f32 v4, s[40:41], v3, v3, 1.0
	v_rcp_f32_e32 v5, v4
	v_cndmask_b32_e32 v0, v195, v1, vcc
	v_and_b32_e32 v7, 0xffff0000, v187
	v_lshlrev_b32_e32 v10, 16, v175
	v_fma_f32 v1, -v4, v5, 1.0
	v_fmac_f32_e32 v5, v1, v5
	v_div_scale_f32 v1, vcc, 1.0, v3, 1.0
	v_mul_f32_e32 v2, v1, v5
	v_fma_f32 v6, -v4, v2, v1
	v_fmac_f32_e32 v2, v6, v5
	v_fma_f32 v1, -v4, v2, v1
	v_div_fmas_f32 v1, v1, v5, v2
	v_div_fixup_f32 v2, v1, v3, 1.0
	v_lshlrev_b32_e32 v1, 16, v186
	v_and_b32_e32 v3, 0xffff0000, v186
	v_mul_f32_e32 v1, 0xbfb8aa3b, v1
	v_exp_f32_e32 v1, v1
	v_mul_f32_e32 v3, 0xbfb8aa3b, v3
	v_exp_f32_e32 v3, v3
	v_lshlrev_b32_e32 v6, 16, v187
	v_add_f32_e32 v1, 1.0, v1
	v_rcp_f32_e32 v4, v1
	v_add_f32_e32 v1, 1.0, v3
	v_rcp_f32_e32 v5, v1
	v_mul_f32_e32 v1, 0xbfb8aa3b, v6
	v_exp_f32_e32 v1, v1
	v_mul_f32_e32 v3, 0xbfb8aa3b, v7
	v_exp_f32_e32 v3, v3
	v_and_b32_e32 v11, 0xffff0000, v175
	v_add_f32_e32 v1, 1.0, v1
	v_rcp_f32_e32 v8, v1
	v_add_f32_e32 v1, 1.0, v3
	v_pk_mul_f32 v[6:7], v[128:129], v[2:3] op_sel_hi:[1,0]
	v_rcp_f32_e32 v9, v1
	v_lshlrev_b32_e32 v1, 16, v174
	v_pk_mul_f32 v[128:129], v[4:5], v[6:7]
	v_pk_mul_f32 v[6:7], v[130:131], v[2:3] op_sel_hi:[1,0]
	v_and_b32_e32 v3, 0xffff0000, v174
	v_mul_f32_e32 v1, 0xbfb8aa3b, v1
	v_exp_f32_e32 v1, v1
	v_mul_f32_e32 v3, 0xbfb8aa3b, v3
	v_exp_f32_e32 v3, v3
	v_pk_mul_f32 v[130:131], v[8:9], v[6:7]
	v_add_f32_e32 v1, 1.0, v1
	v_rcp_f32_e32 v8, v1
	v_add_f32_e32 v1, 1.0, v3
	v_rcp_f32_e32 v9, v1
	v_mul_f32_e32 v1, 0xbfb8aa3b, v10
	v_exp_f32_e32 v1, v1
	v_mul_f32_e32 v3, 0xbfb8aa3b, v11
	v_exp_f32_e32 v3, v3
	v_lshlrev_b32_e32 v14, 16, v173
	v_add_f32_e32 v1, 1.0, v1
	v_rcp_f32_e32 v12, v1
	v_add_f32_e32 v1, 1.0, v3
	v_pk_mul_f32 v[10:11], v[136:137], v[2:3] op_sel_hi:[1,0]
	v_rcp_f32_e32 v13, v1
	v_lshlrev_b32_e32 v1, 16, v172
	v_pk_mul_f32 v[136:137], v[8:9], v[10:11]
	v_pk_mul_f32 v[10:11], v[142:143], v[2:3] op_sel_hi:[1,0]
	v_and_b32_e32 v3, 0xffff0000, v172
	v_mul_f32_e32 v1, 0xbfb8aa3b, v1
	v_exp_f32_e32 v1, v1
	v_mul_f32_e32 v3, 0xbfb8aa3b, v3
	v_exp_f32_e32 v3, v3
	v_pk_mul_f32 v[142:143], v[12:13], v[10:11]
	v_add_f32_e32 v1, 1.0, v1
	v_rcp_f32_e32 v12, v1
	v_add_f32_e32 v1, 1.0, v3
	v_and_b32_e32 v15, 0xffff0000, v173
	v_rcp_f32_e32 v13, v1
	v_mul_f32_e32 v1, 0xbfb8aa3b, v14
	v_exp_f32_e32 v1, v1
	v_mul_f32_e32 v3, 0xbfb8aa3b, v15
	v_exp_f32_e32 v3, v3
	v_pk_mul_f32 v[4:5], v[128:129], v[128:129]
	v_add_f32_e32 v1, 1.0, v1
	v_rcp_f32_e32 v172, v1
	v_add_f32_e32 v1, 1.0, v3
	v_pk_mul_f32 v[14:15], v[148:149], v[2:3] op_sel_hi:[1,0]
	v_rcp_f32_e32 v173, v1
	v_lshlrev_b32_e32 v1, 16, v170
	v_pk_mul_f32 v[148:149], v[12:13], v[14:15]
	v_pk_mul_f32 v[14:15], v[154:155], v[2:3] op_sel_hi:[1,0]
	v_and_b32_e32 v3, 0xffff0000, v170
	v_mul_f32_e32 v1, 0xbfb8aa3b, v1
	v_exp_f32_e32 v1, v1
	v_mul_f32_e32 v3, 0xbfb8aa3b, v3
	v_exp_f32_e32 v3, v3
	v_pk_mul_f32 v[154:155], v[172:173], v[14:15]
	v_add_f32_e32 v1, 1.0, v1
	v_lshlrev_b32_e32 v172, 16, v171
	v_rcp_f32_e32 v170, v1
	v_add_f32_e32 v1, 1.0, v3
	v_and_b32_e32 v173, 0xffff0000, v171
	v_rcp_f32_e32 v171, v1
	v_mul_f32_e32 v1, 0xbfb8aa3b, v172
	v_exp_f32_e32 v1, v1
	v_mul_f32_e32 v3, 0xbfb8aa3b, v173
	v_exp_f32_e32 v3, v3
	v_pk_mul_f32 v[6:7], v[130:131], v[130:131]
	v_add_f32_e32 v1, 1.0, v1
	v_rcp_f32_e32 v172, v1
	v_add_f32_e32 v1, 1.0, v3
	v_rcp_f32_e32 v173, v1
	v_add_f32_e32 v1, v4, v5
	v_add_f32_e32 v1, v6, v1
	v_pk_mul_f32 v[8:9], v[136:137], v[136:137]
	v_add_f32_e32 v1, v7, v1
	v_add_f32_e32 v1, v8, v1
	v_pk_mul_f32 v[10:11], v[142:143], v[142:143]
	v_add_f32_e32 v1, v9, v1
	v_add_f32_e32 v1, v10, v1
	v_pk_mul_f32 v[12:13], v[148:149], v[148:149]
	v_add_f32_e32 v1, v11, v1
	v_add_f32_e32 v1, v12, v1
	v_pk_mul_f32 v[14:15], v[154:155], v[154:155]
	v_pk_mul_f32 v[156:157], v[156:157], v[2:3] op_sel_hi:[1,0]
	v_add_f32_e32 v1, v13, v1
	v_pk_mul_f32 v[156:157], v[170:171], v[156:157]
	v_add_f32_e32 v1, v14, v1
	v_pk_mul_f32 v[170:171], v[156:157], v[156:157]
	v_pk_mul_f32 v[2:3], v[158:159], v[2:3] op_sel_hi:[1,0]
	v_add_f32_e32 v1, v15, v1
	v_pk_mul_f32 v[158:159], v[172:173], v[2:3]
	v_add_f32_e32 v1, v170, v1
	v_pk_mul_f32 v[2:3], v[158:159], v[158:159]
	v_add_f32_e32 v1, v171, v1
	v_add_f32_e32 v1, v2, v1
	v_lshlrev_b32_e32 v0, 2, v0
	v_add_f32_e32 v1, v3, v1
	ds_bpermute_b32 v2, v0, v1
	s_and_saveexec_b64 s[40:41], s[4:5]
	s_cbranch_execz .LBB0_588
	s_waitcnt lgkmcnt(0)
	v_add_f32_e32 v1, v1, v2
	ds_write_b32 v117, v1 offset:62976
